# v13: v12 + EpiZ epilogue stores in saddr form (8 v_mad_i64 and 8 64-bit adds per unit removed; second store of a row uses offset:256)
# baseline (speedup 1.0000x reference)
.LBB0_406:
	v_mov_b32_e32 v2, v138
	v_mov_b32_e32 v132, v139
	s_lshl_b32 s41, s8, 8
	s_or_b32 s41, s41, s27
	s_mul_i32 s43, s29, 0x1a0000
	v_lshl_add_u32 v132, v132, 3, s41
	s_mul_hi_i32 s41, s29, 0x1a0000
	s_add_u32 s44, s19, s43
	s_addc_u32 s45, s20, s41
	s_lshl_b32 s41, s29, 8
	s_and_b32 s41, s41, 0x400
	s_add_i32 s41, s41, 0
	v_add_u32_e32 v144, s26, v2
	v_lshl_add_u32 v2, v144, 2, s41
	v_add_u32_e32 v145, 0x24400, v2
	ds_read_b32 v2, v145
	s_cmp_lt_i32 s8, 2
	s_cselect_b64 vcc, -1, 0
	v_mov_b32_e32 v133, 0x3e38aa3b
	v_cndmask_b32_e32 v146, 1.0, v133, vcc
	s_waitcnt lgkmcnt(0)
	v_mul_f32_e32 v2, v146, v2
	v_mul_u32_u24_e32 v133, 0x1200, v144
	v_pk_mul_f32 v[130:131], v[130:131], v[2:3] op_sel_hi:[1,0]
	v_pk_mul_f32 v[128:129], v[128:129], v[2:3] op_sel_hi:[1,0]
	v_pk_mul_f32 v[142:143], v[122:123], v[2:3] op_sel_hi:[1,0]
	v_pk_mul_f32 v[122:123], v[120:121], v[2:3] op_sel_hi:[1,0]
	v_lshl_add_u32 v132, v132, 1, v133
	v_cvt_pk_bf16_f32 v120, v128, v129
	v_cvt_pk_bf16_f32 v121, v130, v131
	v_cvt_pk_bf16_f32 v122, v122, v123
	v_cvt_pk_bf16_f32 v123, v142, v143
	global_store_dwordx4 v132, v[120:123], s[44:45] sc1
	s_nop 1
	v_pk_mul_f32 v[120:121], v[126:127], v[2:3] op_sel_hi:[1,0]
	v_pk_mul_f32 v[122:123], v[124:125], v[2:3] op_sel_hi:[1,0]
	v_pk_mul_f32 v[124:125], v[118:119], v[2:3] op_sel_hi:[1,0]
	v_pk_mul_f32 v[118:119], v[116:117], v[2:3] op_sel_hi:[1,0]
	s_mov_b64 s[50:51], 0x100
	v_cvt_pk_bf16_f32 v116, v122, v123
	v_cvt_pk_bf16_f32 v117, v120, v121
	v_cvt_pk_bf16_f32 v118, v118, v119
	v_cvt_pk_bf16_f32 v119, v124, v125
	global_store_dwordx4 v132, v[116:119], s[44:45] offset:256 sc1
	s_nop 1
	ds_read_b32 v2, v145 offset:64
	v_add_u32_e32 v240, 0x12000, v132
	s_cmp_eq_u32 s80, s29
	s_mov_b64 s[80:81], -1
	s_waitcnt lgkmcnt(0)
	v_mul_f32_e32 v2, v146, v2
	v_pk_mul_f32 v[114:115], v[114:115], v[2:3] op_sel_hi:[1,0]
	v_pk_mul_f32 v[112:113], v[112:113], v[2:3] op_sel_hi:[1,0]
	v_pk_mul_f32 v[116:117], v[106:107], v[2:3] op_sel_hi:[1,0]
	v_pk_mul_f32 v[106:107], v[104:105], v[2:3] op_sel_hi:[1,0]
	v_cvt_pk_bf16_f32 v104, v112, v113
	v_cvt_pk_bf16_f32 v105, v114, v115
	v_cvt_pk_bf16_f32 v106, v106, v107
	v_cvt_pk_bf16_f32 v107, v116, v117
	global_store_dwordx4 v240, v[104:107], s[44:45] sc1
	s_nop 1
	v_pk_mul_f32 v[104:105], v[110:111], v[2:3] op_sel_hi:[1,0]
	v_pk_mul_f32 v[106:107], v[108:109], v[2:3] op_sel_hi:[1,0]
	v_pk_mul_f32 v[108:109], v[102:103], v[2:3] op_sel_hi:[1,0]
	v_pk_mul_f32 v[102:103], v[100:101], v[2:3] op_sel_hi:[1,0]
	v_cvt_pk_bf16_f32 v100, v106, v107
	v_cvt_pk_bf16_f32 v101, v104, v105
	v_cvt_pk_bf16_f32 v102, v102, v103
	v_cvt_pk_bf16_f32 v103, v108, v109
	global_store_dwordx4 v240, v[100:103], s[44:45] offset:256 sc1
	s_nop 1
	ds_read_b32 v2, v145 offset:128
	v_add_u32_e32 v241, 0x24000, v132
	s_waitcnt lgkmcnt(0)
	v_mul_f32_e32 v2, v146, v2
	v_pk_mul_f32 v[98:99], v[98:99], v[2:3] op_sel_hi:[1,0]
	v_pk_mul_f32 v[96:97], v[96:97], v[2:3] op_sel_hi:[1,0]
	v_pk_mul_f32 v[100:101], v[90:91], v[2:3] op_sel_hi:[1,0]
	v_pk_mul_f32 v[90:91], v[88:89], v[2:3] op_sel_hi:[1,0]
	v_cvt_pk_bf16_f32 v88, v96, v97
	v_cvt_pk_bf16_f32 v89, v98, v99
	v_cvt_pk_bf16_f32 v90, v90, v91
	v_cvt_pk_bf16_f32 v91, v100, v101
	global_store_dwordx4 v241, v[88:91], s[44:45] sc1
	s_nop 1
	v_pk_mul_f32 v[88:89], v[94:95], v[2:3] op_sel_hi:[1,0]
	v_pk_mul_f32 v[90:91], v[92:93], v[2:3] op_sel_hi:[1,0]
	v_pk_mul_f32 v[92:93], v[86:87], v[2:3] op_sel_hi:[1,0]
	v_pk_mul_f32 v[86:87], v[84:85], v[2:3] op_sel_hi:[1,0]
	v_cvt_pk_bf16_f32 v84, v90, v91
	v_cvt_pk_bf16_f32 v85, v88, v89
	v_cvt_pk_bf16_f32 v86, v86, v87
	v_cvt_pk_bf16_f32 v87, v92, v93
	global_store_dwordx4 v241, v[84:87], s[44:45] offset:256 sc1
	s_nop 1
	ds_read_b32 v2, v145 offset:192
	v_add_u32_e32 v242, 0x36000, v132
	s_waitcnt lgkmcnt(0)
	v_mul_f32_e32 v2, v146, v2
	v_pk_mul_f32 v[66:67], v[66:67], v[2:3] op_sel_hi:[1,0]
	v_pk_mul_f32 v[64:65], v[64:65], v[2:3] op_sel_hi:[1,0]
	v_pk_mul_f32 v[84:85], v[58:59], v[2:3] op_sel_hi:[1,0]
	v_pk_mul_f32 v[58:59], v[56:57], v[2:3] op_sel_hi:[1,0]
	v_cvt_pk_bf16_f32 v56, v64, v65
	v_cvt_pk_bf16_f32 v57, v66, v67
	v_cvt_pk_bf16_f32 v58, v58, v59
	v_cvt_pk_bf16_f32 v59, v84, v85
	global_store_dwordx4 v242, v[56:59], s[44:45] sc1
	s_nop 1
	v_pk_mul_f32 v[56:57], v[62:63], v[2:3] op_sel_hi:[1,0]
	v_pk_mul_f32 v[58:59], v[60:61], v[2:3] op_sel_hi:[1,0]
	v_pk_mul_f32 v[60:61], v[54:55], v[2:3] op_sel_hi:[1,0]
	v_pk_mul_f32 v[54:55], v[52:53], v[2:3] op_sel_hi:[1,0]
	v_cvt_pk_bf16_f32 v52, v58, v59
	v_cvt_pk_bf16_f32 v53, v56, v57
	v_cvt_pk_bf16_f32 v54, v54, v55
	v_cvt_pk_bf16_f32 v55, v60, v61
	global_store_dwordx4 v242, v[52:55], s[44:45] offset:256 sc1
	s_nop 1
	ds_read_b32 v2, v145 offset:512
	v_add_u32_e32 v243, 0x90000, v132
	s_waitcnt lgkmcnt(0)
	v_mul_f32_e32 v2, v146, v2
	v_pk_mul_f32 v[54:55], v[82:83], v[2:3] op_sel_hi:[1,0]
	v_pk_mul_f32 v[52:53], v[80:81], v[2:3] op_sel_hi:[1,0]
	v_pk_mul_f32 v[56:57], v[74:75], v[2:3] op_sel_hi:[1,0]
	v_pk_mul_f32 v[58:59], v[72:73], v[2:3] op_sel_hi:[1,0]
	v_cvt_pk_bf16_f32 v52, v52, v53
	v_cvt_pk_bf16_f32 v53, v54, v55
	v_cvt_pk_bf16_f32 v54, v58, v59
	v_cvt_pk_bf16_f32 v55, v56, v57
	global_store_dwordx4 v243, v[52:55], s[44:45] sc1
	s_nop 1
	v_pk_mul_f32 v[54:55], v[78:79], v[2:3] op_sel_hi:[1,0]
	v_pk_mul_f32 v[52:53], v[76:77], v[2:3] op_sel_hi:[1,0]
	v_pk_mul_f32 v[58:59], v[70:71], v[2:3] op_sel_hi:[1,0]
	v_pk_mul_f32 v[60:61], v[68:69], v[2:3] op_sel_hi:[1,0]
	v_cvt_pk_bf16_f32 v52, v52, v53
	v_cvt_pk_bf16_f32 v53, v54, v55
	v_cvt_pk_bf16_f32 v54, v60, v61
	v_cvt_pk_bf16_f32 v55, v58, v59
	global_store_dwordx4 v243, v[52:55], s[44:45] offset:256 sc1
	s_nop 1
	ds_read_b32 v2, v145 offset:576
	v_add_u32_e32 v244, 0xa2000, v132
	s_waitcnt lgkmcnt(0)
	v_mul_f32_e32 v2, v146, v2
	v_pk_mul_f32 v[50:51], v[50:51], v[2:3] op_sel_hi:[1,0]
	v_pk_mul_f32 v[48:49], v[48:49], v[2:3] op_sel_hi:[1,0]
	v_pk_mul_f32 v[52:53], v[42:43], v[2:3] op_sel_hi:[1,0]
	v_pk_mul_f32 v[42:43], v[40:41], v[2:3] op_sel_hi:[1,0]
	v_cvt_pk_bf16_f32 v40, v48, v49
	v_cvt_pk_bf16_f32 v41, v50, v51
	v_cvt_pk_bf16_f32 v42, v42, v43
	v_cvt_pk_bf16_f32 v43, v52, v53
	global_store_dwordx4 v244, v[40:43], s[44:45] sc1
	s_nop 1
	v_pk_mul_f32 v[40:41], v[46:47], v[2:3] op_sel_hi:[1,0]
	v_pk_mul_f32 v[42:43], v[44:45], v[2:3] op_sel_hi:[1,0]
	v_pk_mul_f32 v[44:45], v[38:39], v[2:3] op_sel_hi:[1,0]
	v_pk_mul_f32 v[38:39], v[36:37], v[2:3] op_sel_hi:[1,0]
	v_cvt_pk_bf16_f32 v36, v42, v43
	v_cvt_pk_bf16_f32 v37, v40, v41
	v_cvt_pk_bf16_f32 v38, v38, v39
	v_cvt_pk_bf16_f32 v39, v44, v45
	global_store_dwordx4 v244, v[36:39], s[44:45] offset:256 sc1
	s_nop 1
	ds_read_b32 v2, v145 offset:640
	v_add_u32_e32 v245, 0xb4000, v132
	s_waitcnt lgkmcnt(0)
	v_mul_f32_e32 v2, v146, v2
	v_pk_mul_f32 v[34:35], v[34:35], v[2:3] op_sel_hi:[1,0]
	v_pk_mul_f32 v[32:33], v[32:33], v[2:3] op_sel_hi:[1,0]
	v_pk_mul_f32 v[36:37], v[26:27], v[2:3] op_sel_hi:[1,0]
	v_pk_mul_f32 v[26:27], v[24:25], v[2:3] op_sel_hi:[1,0]
	v_cvt_pk_bf16_f32 v24, v32, v33
	v_cvt_pk_bf16_f32 v25, v34, v35
	v_cvt_pk_bf16_f32 v26, v26, v27
	v_cvt_pk_bf16_f32 v27, v36, v37
	global_store_dwordx4 v245, v[24:27], s[44:45] sc1
	s_nop 1
	v_pk_mul_f32 v[24:25], v[30:31], v[2:3] op_sel_hi:[1,0]
	v_pk_mul_f32 v[26:27], v[28:29], v[2:3] op_sel_hi:[1,0]
	v_pk_mul_f32 v[28:29], v[22:23], v[2:3] op_sel_hi:[1,0]
	v_pk_mul_f32 v[22:23], v[20:21], v[2:3] op_sel_hi:[1,0]
	v_cvt_pk_bf16_f32 v20, v26, v27
	v_cvt_pk_bf16_f32 v21, v24, v25
	v_cvt_pk_bf16_f32 v22, v22, v23
	v_cvt_pk_bf16_f32 v23, v28, v29
	global_store_dwordx4 v245, v[20:23], s[44:45] offset:256 sc1
	s_nop 1
	ds_read_b32 v2, v145 offset:704
	v_add_u32_e32 v246, 0xc6000, v132
	s_waitcnt lgkmcnt(0)
	v_mul_f32_e32 v2, v146, v2
	v_pk_mul_f32 v[18:19], v[18:19], v[2:3] op_sel_hi:[1,0]
	v_pk_mul_f32 v[16:17], v[16:17], v[2:3] op_sel_hi:[1,0]
	v_pk_mul_f32 v[20:21], v[10:11], v[2:3] op_sel_hi:[1,0]
	v_pk_mul_f32 v[10:11], v[8:9], v[2:3] op_sel_hi:[1,0]
	v_cvt_pk_bf16_f32 v8, v16, v17
	v_cvt_pk_bf16_f32 v9, v18, v19
	v_cvt_pk_bf16_f32 v10, v10, v11
	v_cvt_pk_bf16_f32 v11, v20, v21
	global_store_dwordx4 v246, v[8:11], s[44:45] sc1
	s_nop 1
	v_pk_mul_f32 v[8:9], v[14:15], v[2:3] op_sel_hi:[1,0]
	v_pk_mul_f32 v[10:11], v[12:13], v[2:3] op_sel_hi:[1,0]
	v_pk_mul_f32 v[12:13], v[6:7], v[2:3] op_sel_hi:[1,0]
	v_pk_mul_f32 v[6:7], v[4:5], v[2:3] op_sel_hi:[1,0]
	v_cvt_pk_bf16_f32 v4, v10, v11
	v_cvt_pk_bf16_f32 v5, v8, v9
	v_cvt_pk_bf16_f32 v6, v6, v7
	v_cvt_pk_bf16_f32 v7, v12, v13
	global_store_dwordx4 v246, v[4:7], s[44:45] offset:256 sc1
	s_nop 1
	s_cselect_b64 s[44:45], -1, 0
	s_and_b64 s[44:45], s[76:77], s[44:45]
	s_andn2_b64 vcc, exec, s[44:45]
	s_cbranch_vccz .LBB0_410
	s_waitcnt vmcnt(0)
	s_mov_b64 s[80:81], exec
	v_readlane_b32 s44, v255, 11
	v_readlane_b32 s45, v255, 12
	s_and_b64 s[44:45], s[80:81], s[44:45]
	s_mov_b64 exec, s[44:45]
	s_cbranch_execz .LBB0_409
	s_lshl_b32 s41, s29, 6
	s_add_i32 s44, s41, 0x3000
	s_ashr_i32 s45, s44, 31
	s_add_i32 s43, s40, 1
	s_lshl_b64 s[44:45], s[44:45], 2
	v_readlane_b32 s41, v255, 5
	s_add_u32 s44, s41, s44
	v_readlane_b32 s41, v255, 6
	s_addc_u32 s45, s41, s45
	v_mov_b32_e32 v2, s43
	global_atomic_add v3, v2, s[44:45]
